# hand-written x->bf16 conversion loop in P0 (4 rows per iteration); plus final norm, peel, epilogue fast paths, LRU prefetch, sc1
# baseline (speedup 1.0000x reference)
; __device__ __forceinline__ unsigned cvt_pk_bf16(float lo, float hi) { unsigned r; asm volatile("v_cvt_pk_bf16_f32 %0, %1, %2" : "=v"(r) : "v"(lo), "v"(hi)); return r; }
; __global__ void __launch_bounds__(512, 2) fwd_mega(Args a) {
;     ...
;     for (int row = gw; row < M; row += NGW) {
;         const f32x4* xr = (const f32x4*)(a.x + (size_t)row * D) + lane; float s = 0.f;
; #pragma unroll
;         for (int j = 0; j < 4; ++j) { const f32x4 v = xr[64 * j]; s += (v[0] * v[0] + v[1] * v[1]) + (v[2] * v[2] + v[3] * v[3]);
;             u32x2 o; o.x = cvt_pk_bf16(v[0], v[1]); o.y = cvt_pk_bf16(v[2], v[3]); *((u32x2*)(XB + (size_t)row * D) + lane + 64 * j) = o; }
;         s = wave_sum(s); if (lane < 16) SS[(size_t)row * 16 + lane] = lane == 0 ? s : 0.f;
.LBB0_74:
	v_lshlrev_b32_e32 v50, 4, v38
	v_lshlrev_b32_e32 v51, 3, v38
	v_lshlrev_b32_e32 v52, 2, v38
	s_mov_b32 s10, s6
	s_lshl_b32 s8, s10, 12
	s_add_u32 s4, s68, s8
	s_addc_u32 s5, s69, 0
	global_load_dwordx4 v[56:59], v50, s[4:5]
	global_load_dwordx4 v[60:63], v50, s[4:5] offset:1024
	global_load_dwordx4 v[64:67], v50, s[4:5] offset:2048
	global_load_dwordx4 v[68:71], v50, s[4:5] offset:3072
	s_mul_i32 s11, s44, 1
	s_add_i32 s11, s11, s6
	s_cmp_gt_i32 s11, 0x3fff
	s_cselect_b32 s11, s6, s11
	s_lshl_b32 s8, s11, 12
	s_add_u32 s4, s68, s8
	s_addc_u32 s5, s69, 0
	global_load_dwordx4 v[72:75], v50, s[4:5]
	global_load_dwordx4 v[76:79], v50, s[4:5] offset:1024
	global_load_dwordx4 v[80:83], v50, s[4:5] offset:2048
	global_load_dwordx4 v[84:87], v50, s[4:5] offset:3072
	s_mul_i32 s12, s44, 2
	s_add_i32 s12, s12, s6
	s_cmp_gt_i32 s12, 0x3fff
	s_cselect_b32 s12, s6, s12
	s_lshl_b32 s8, s12, 12
	s_add_u32 s4, s68, s8
	s_addc_u32 s5, s69, 0
	global_load_dwordx4 v[88:91], v50, s[4:5]
	global_load_dwordx4 v[92:95], v50, s[4:5] offset:1024
	global_load_dwordx4 v[96:99], v50, s[4:5] offset:2048
	global_load_dwordx4 v[100:103], v50, s[4:5] offset:3072
	s_mul_i32 s13, s44, 3
	s_add_i32 s13, s13, s6
	s_cmp_gt_i32 s13, 0x3fff
	s_cselect_b32 s13, s6, s13
	s_lshl_b32 s8, s13, 12
	s_add_u32 s4, s68, s8
	s_addc_u32 s5, s69, 0
	global_load_dwordx4 v[104:107], v50, s[4:5]
	global_load_dwordx4 v[108:111], v50, s[4:5] offset:1024
	global_load_dwordx4 v[112:115], v50, s[4:5] offset:2048
	global_load_dwordx4 v[116:119], v50, s[4:5] offset:3072
	s_waitcnt vmcnt(12)
	s_lshl_b32 s8, s10, 11
	s_add_u32 s4, s64, s8
	s_addc_u32 s5, s65, 0
	s_add_u32 s4, s4, 0x6280000
	s_addc_u32 s5, s5, 0
	v_cvt_pk_bf16_f32 v122, v56, v57
	v_cvt_pk_bf16_f32 v123, v58, v59
	global_store_dwordx2 v51, v[122:123], s[4:5] sc1
	v_mul_f32_e32 v120, v57, v57
	v_mul_f32_e32 v121, v59, v59
	v_fmac_f32_e32 v120, v56, v56
	v_fmac_f32_e32 v121, v58, v58
	v_add_f32_e32 v124, v120, v121
	v_cvt_pk_bf16_f32 v122, v60, v61
	v_cvt_pk_bf16_f32 v123, v62, v63
	global_store_dwordx2 v51, v[122:123], s[4:5] offset:512 sc1
	v_mul_f32_e32 v120, v61, v61
	v_mul_f32_e32 v121, v63, v63
	v_fmac_f32_e32 v120, v60, v60
	v_fmac_f32_e32 v121, v62, v62
	v_add_f32_e32 v120, v120, v121
	v_add_f32_e32 v124, v124, v120
	v_cvt_pk_bf16_f32 v122, v64, v65
	v_cvt_pk_bf16_f32 v123, v66, v67
	global_store_dwordx2 v51, v[122:123], s[4:5] offset:1024 sc1
	v_mul_f32_e32 v120, v65, v65
	v_mul_f32_e32 v121, v67, v67
	v_fmac_f32_e32 v120, v64, v64
	v_fmac_f32_e32 v121, v66, v66
	v_add_f32_e32 v120, v120, v121
	v_add_f32_e32 v124, v124, v120
	v_cvt_pk_bf16_f32 v122, v68, v69
	v_cvt_pk_bf16_f32 v123, v70, v71
	global_store_dwordx2 v51, v[122:123], s[4:5] offset:1536 sc1
	v_mul_f32_e32 v120, v69, v69
	v_mul_f32_e32 v121, v71, v71
	v_fmac_f32_e32 v120, v68, v68
	v_fmac_f32_e32 v121, v70, v70
	v_add_f32_e32 v120, v120, v121
	v_add_f32_e32 v124, v124, v120
	s_waitcnt vmcnt(12)
	s_lshl_b32 s8, s11, 11
	s_add_u32 s4, s64, s8
	s_addc_u32 s5, s65, 0
	s_add_u32 s4, s4, 0x6280000
	s_addc_u32 s5, s5, 0
	v_cvt_pk_bf16_f32 v122, v72, v73
	v_cvt_pk_bf16_f32 v123, v74, v75
	global_store_dwordx2 v51, v[122:123], s[4:5] sc1
	v_mul_f32_e32 v120, v73, v73
	v_mul_f32_e32 v121, v75, v75
	v_fmac_f32_e32 v120, v72, v72
	v_fmac_f32_e32 v121, v74, v74
	v_add_f32_e32 v125, v120, v121
	v_cvt_pk_bf16_f32 v122, v76, v77
	v_cvt_pk_bf16_f32 v123, v78, v79
	global_store_dwordx2 v51, v[122:123], s[4:5] offset:512 sc1
	v_mul_f32_e32 v120, v77, v77
	v_mul_f32_e32 v121, v79, v79
	v_fmac_f32_e32 v120, v76, v76
	v_fmac_f32_e32 v121, v78, v78
	v_add_f32_e32 v120, v120, v121
	v_add_f32_e32 v125, v125, v120
	v_cvt_pk_bf16_f32 v122, v80, v81
	v_cvt_pk_bf16_f32 v123, v82, v83
	global_store_dwordx2 v51, v[122:123], s[4:5] offset:1024 sc1
	v_mul_f32_e32 v120, v81, v81
	v_mul_f32_e32 v121, v83, v83
	v_fmac_f32_e32 v120, v80, v80
	v_fmac_f32_e32 v121, v82, v82
	v_add_f32_e32 v120, v120, v121
	v_add_f32_e32 v125, v125, v120
	v_cvt_pk_bf16_f32 v122, v84, v85
	v_cvt_pk_bf16_f32 v123, v86, v87
	global_store_dwordx2 v51, v[122:123], s[4:5] offset:1536 sc1
	v_mul_f32_e32 v120, v85, v85
	v_mul_f32_e32 v121, v87, v87
	v_fmac_f32_e32 v120, v84, v84
	v_fmac_f32_e32 v121, v86, v86
	v_add_f32_e32 v120, v120, v121
	v_add_f32_e32 v125, v125, v120
	s_waitcnt vmcnt(12)
	s_lshl_b32 s8, s12, 11
	s_add_u32 s4, s64, s8
	s_addc_u32 s5, s65, 0
	s_add_u32 s4, s4, 0x6280000
	s_addc_u32 s5, s5, 0
	v_cvt_pk_bf16_f32 v122, v88, v89
	v_cvt_pk_bf16_f32 v123, v90, v91
	global_store_dwordx2 v51, v[122:123], s[4:5] sc1
	v_mul_f32_e32 v120, v89, v89
	v_mul_f32_e32 v121, v91, v91
	v_fmac_f32_e32 v120, v88, v88
	v_fmac_f32_e32 v121, v90, v90
	v_add_f32_e32 v126, v120, v121
	v_cvt_pk_bf16_f32 v122, v92, v93
	v_cvt_pk_bf16_f32 v123, v94, v95
	global_store_dwordx2 v51, v[122:123], s[4:5] offset:512 sc1
	v_mul_f32_e32 v120, v93, v93
	v_mul_f32_e32 v121, v95, v95
	v_fmac_f32_e32 v120, v92, v92
	v_fmac_f32_e32 v121, v94, v94
	v_add_f32_e32 v120, v120, v121
	v_add_f32_e32 v126, v126, v120
	v_cvt_pk_bf16_f32 v122, v96, v97
	v_cvt_pk_bf16_f32 v123, v98, v99
	global_store_dwordx2 v51, v[122:123], s[4:5] offset:1024 sc1
	v_mul_f32_e32 v120, v97, v97
	v_mul_f32_e32 v121, v99, v99
	v_fmac_f32_e32 v120, v96, v96
	v_fmac_f32_e32 v121, v98, v98
	v_add_f32_e32 v120, v120, v121
	v_add_f32_e32 v126, v126, v120
	v_cvt_pk_bf16_f32 v122, v100, v101
	v_cvt_pk_bf16_f32 v123, v102, v103
	global_store_dwordx2 v51, v[122:123], s[4:5] offset:1536 sc1
	v_mul_f32_e32 v120, v101, v101
	v_mul_f32_e32 v121, v103, v103
	v_fmac_f32_e32 v120, v100, v100
	v_fmac_f32_e32 v121, v102, v102
	v_add_f32_e32 v120, v120, v121
	v_add_f32_e32 v126, v126, v120
	s_waitcnt vmcnt(12)
; __device__ __forceinline__ unsigned cvt_pk_bf16(float lo, float hi) { unsigned r; asm volatile("v_cvt_pk_bf16_f32 %0, %1, %2" : "=v"(r) : "v"(lo), "v"(hi)); return r; }
; __device__ __forceinline__ float wave_sum(float v) {
; #pragma unroll
;     for (int o = 1; o < 64; o <<= 1) v += __shfl_xor(v, o);
;     return v;
; }
; __global__ void __launch_bounds__(512, 2) fwd_mega(Args a) {
;     ...
;     for (int row = gw; row < M; row += NGW) {
;         const f32x4* xr = (const f32x4*)(a.x + (size_t)row * D) + lane; float s = 0.f;
; #pragma unroll
;         for (int j = 0; j < 4; ++j) { const f32x4 v = xr[64 * j]; s += (v[0] * v[0] + v[1] * v[1]) + (v[2] * v[2] + v[3] * v[3]);
;             u32x2 o; o.x = cvt_pk_bf16(v[0], v[1]); o.y = cvt_pk_bf16(v[2], v[3]); *((u32x2*)(XB + (size_t)row * D) + lane + 64 * j) = o; }
;         s = wave_sum(s); if (lane < 16) SS[(size_t)row * 16 + lane] = lane == 0 ? s : 0.f;
;     }
	s_lshl_b32 s8, s13, 11
	s_add_u32 s4, s64, s8
	s_addc_u32 s5, s65, 0
	s_add_u32 s4, s4, 0x6280000
	s_addc_u32 s5, s5, 0
	v_cvt_pk_bf16_f32 v122, v104, v105
	v_cvt_pk_bf16_f32 v123, v106, v107
	global_store_dwordx2 v51, v[122:123], s[4:5] sc1
	v_mul_f32_e32 v120, v105, v105
	v_mul_f32_e32 v121, v107, v107
	v_fmac_f32_e32 v120, v104, v104
	v_fmac_f32_e32 v121, v106, v106
	v_add_f32_e32 v127, v120, v121
	v_cvt_pk_bf16_f32 v122, v108, v109
	v_cvt_pk_bf16_f32 v123, v110, v111
	global_store_dwordx2 v51, v[122:123], s[4:5] offset:512 sc1
	v_mul_f32_e32 v120, v109, v109
	v_mul_f32_e32 v121, v111, v111
	v_fmac_f32_e32 v120, v108, v108
	v_fmac_f32_e32 v121, v110, v110
	v_add_f32_e32 v120, v120, v121
	v_add_f32_e32 v127, v127, v120
	v_cvt_pk_bf16_f32 v122, v112, v113
	v_cvt_pk_bf16_f32 v123, v114, v115
	global_store_dwordx2 v51, v[122:123], s[4:5] offset:1024 sc1
	v_mul_f32_e32 v120, v113, v113
	v_mul_f32_e32 v121, v115, v115
	v_fmac_f32_e32 v120, v112, v112
	v_fmac_f32_e32 v121, v114, v114
	v_add_f32_e32 v120, v120, v121
	v_add_f32_e32 v127, v127, v120
	v_cvt_pk_bf16_f32 v122, v116, v117
	v_cvt_pk_bf16_f32 v123, v118, v119
	global_store_dwordx2 v51, v[122:123], s[4:5] offset:1536 sc1
	v_mul_f32_e32 v120, v117, v117
	v_mul_f32_e32 v121, v119, v119
	v_fmac_f32_e32 v120, v116, v116
	v_fmac_f32_e32 v121, v118, v118
	v_add_f32_e32 v120, v120, v121
	v_add_f32_e32 v127, v127, v120
	v_xor_b32_e32 v128, 1, v38
	v_lshlrev_b32_e32 v128, 2, v128
	ds_bpermute_b32 v134, v128, v124
	ds_bpermute_b32 v135, v128, v125
	ds_bpermute_b32 v136, v128, v126
	ds_bpermute_b32 v137, v128, v127
	s_waitcnt lgkmcnt(0)
	v_add_f32_e32 v124, v124, v134
	v_add_f32_e32 v125, v125, v135
	v_add_f32_e32 v126, v126, v136
	v_add_f32_e32 v127, v127, v137
	v_xor_b32_e32 v128, 2, v38
	v_lshlrev_b32_e32 v128, 2, v128
	ds_bpermute_b32 v134, v128, v124
	ds_bpermute_b32 v135, v128, v125
	ds_bpermute_b32 v136, v128, v126
	ds_bpermute_b32 v137, v128, v127
	s_waitcnt lgkmcnt(0)
	v_add_f32_e32 v124, v124, v134
	v_add_f32_e32 v125, v125, v135
	v_add_f32_e32 v126, v126, v136
	v_add_f32_e32 v127, v127, v137
	v_xor_b32_e32 v128, 4, v38
	v_lshlrev_b32_e32 v128, 2, v128
	ds_bpermute_b32 v134, v128, v124
	ds_bpermute_b32 v135, v128, v125
	ds_bpermute_b32 v136, v128, v126
	ds_bpermute_b32 v137, v128, v127
	s_waitcnt lgkmcnt(0)
	v_add_f32_e32 v124, v124, v134
	v_add_f32_e32 v125, v125, v135
	v_add_f32_e32 v126, v126, v136
	v_add_f32_e32 v127, v127, v137
	v_xor_b32_e32 v128, 8, v38
	v_lshlrev_b32_e32 v128, 2, v128
	ds_bpermute_b32 v134, v128, v124
	ds_bpermute_b32 v135, v128, v125
	ds_bpermute_b32 v136, v128, v126
	ds_bpermute_b32 v137, v128, v127
	s_waitcnt lgkmcnt(0)
	v_add_f32_e32 v124, v124, v134
	v_add_f32_e32 v125, v125, v135
	v_add_f32_e32 v126, v126, v136
	v_add_f32_e32 v127, v127, v137
	v_xor_b32_e32 v128, 16, v38
	v_lshlrev_b32_e32 v128, 2, v128
	ds_bpermute_b32 v134, v128, v124
	ds_bpermute_b32 v135, v128, v125
	ds_bpermute_b32 v136, v128, v126
	ds_bpermute_b32 v137, v128, v127
	s_waitcnt lgkmcnt(0)
	v_add_f32_e32 v124, v124, v134
	v_add_f32_e32 v125, v125, v135
	v_add_f32_e32 v126, v126, v136
	v_add_f32_e32 v127, v127, v137
	v_xor_b32_e32 v128, 32, v38
	v_lshlrev_b32_e32 v128, 2, v128
	ds_bpermute_b32 v134, v128, v124
	ds_bpermute_b32 v135, v128, v125
	ds_bpermute_b32 v136, v128, v126
	ds_bpermute_b32 v137, v128, v127
	s_waitcnt lgkmcnt(0)
	v_add_f32_e32 v124, v124, v134
	v_add_f32_e32 v125, v125, v135
	v_add_f32_e32 v126, v126, v136
	v_add_f32_e32 v127, v127, v137
	v_cmp_eq_u32_e64 s[8:9], 0, v38
	v_cmp_gt_u32_e32 vcc, 16, v38
	s_nop 1
	v_cndmask_b32_e64 v124, 0, v124, s[8:9]
	v_cndmask_b32_e64 v125, 0, v125, s[8:9]
	v_cndmask_b32_e64 v126, 0, v126, s[8:9]
	v_cndmask_b32_e64 v127, 0, v127, s[8:9]
	s_and_saveexec_b64 s[8:9], vcc
	s_lshl_b32 s4, s10, 6
	s_add_u32 s4, s64, s4
	s_addc_u32 s5, s65, 0
	s_add_u32 s4, s4, 0x17a80000
	s_addc_u32 s5, s5, 0
	global_store_dword v52, v124, s[4:5] sc1
	s_lshl_b32 s4, s11, 6
	s_add_u32 s4, s64, s4
	s_addc_u32 s5, s65, 0
	s_add_u32 s4, s4, 0x17a80000
	s_addc_u32 s5, s5, 0
	global_store_dword v52, v125, s[4:5] sc1
	s_lshl_b32 s4, s12, 6
	s_add_u32 s4, s64, s4
	s_addc_u32 s5, s65, 0
	s_add_u32 s4, s4, 0x17a80000
	s_addc_u32 s5, s5, 0
	global_store_dword v52, v126, s[4:5] sc1
	s_lshl_b32 s4, s13, 6
	s_add_u32 s4, s64, s4
	s_addc_u32 s5, s65, 0
	s_add_u32 s4, s4, 0x17a80000
	s_addc_u32 s5, s5, 0
	global_store_dword v52, v127, s[4:5] sc1
	s_or_b64 exec, exec, s[8:9]
	s_mul_i32 s4, s44, 4
	s_add_i32 s6, s6, s4
	s_cmpk_gt_i32 s6, 0x3fff
	s_cbranch_scc0 .LBB0_74
